# MLP down-projection epilogue: residual loads of row groups 1 and 2 issued with group 0's at the epilogue start (into dead fragment registers), counted waits vmcnt(8)
# speedup vs baseline: 1.0015x; 1.0015x over previous
;     __device__ __forceinline__ void operator()(const f32x4 (&acc)[2][2][4][2], const Unit& u, int wr, int wc, int fr, int fq, int) const {
;         const int row0 = u.pm * BM + wr * 64 + fr, col0 = u.pn * BM + wc * 64 + 8 * fq;
;         const float* Xin = (u.pm * BM < split) ? Xin0 : Xin1 - (size_t)split * ldc;
; #pragma unroll
;         for (int am = 0; am < 4; ++am) { const int ai = am >> 1, m0 = (am & 1) * 2;
;             f32x4 xf[2][2][2]; u32x4 xr[2][2];
;             if (Xin0) {
; #pragma unroll
;                 for (int mm = 0; mm < 2; ++mm) { const size_t ro = (size_t)(row0 + ai * HALF + (m0 + mm) * 16) * ldc + col0;
; #pragma unroll
;                     for (int bj = 0; bj < 2; ++bj) { xf[mm][bj][0] = *(const f32x4*)(Xin + ro + bj * 32); xf[mm][bj][1] = *(const f32x4*)(Xin + ro + bj * 32 + 4); } }
;             } else {
; #pragma unroll
;                 for (int mm = 0; mm < 2; ++mm)
; #pragma unroll
;                     for (int bj = 0; bj < 2; ++bj) xr[mm][bj] = *(const u32x4*)(XB + (size_t)(row0 + ai * HALF + (m0 + mm) * 16) * ldc + col0 + bj * 32);
;             }
;             asm volatile("" ::: "memory");
; #pragma unroll
;             for (int mm = 0; mm < 2; ++mm) { const int m = m0 + mm; const int row = row0 + ai * HALF + m * 16; const size_t ro = (size_t)row * ldc + col0; float ss = 0.f;
; #pragma unroll
;                 for (int bj = 0; bj < 2; ++bj) { f32x4 x0, x1;
;                     if (Xin0) { x0 = xf[mm][bj][0]; x1 = xf[mm][bj][1]; }
;                     else { const u32x4 w = xr[mm][bj];
;                         x0 = (f32x4){__uint_as_float(w.x << 16), __uint_as_float(w.x & 0xffff0000u), __uint_as_float(w.y << 16), __uint_as_float(w.y & 0xffff0000u)};
;                         x1 = (f32x4){__uint_as_float(w.z << 16), __uint_as_float(w.z & 0xffff0000u), __uint_as_float(w.w << 16), __uint_as_float(w.w & 0xffff0000u)}; }
;                     x0 = x0 + acc[ai][bj][m][0]; x1 = x1 + acc[ai][bj][m][1];
;                     if (Xout) { *(f32x4*)(Xout + ro + bj * 32) = x0; *(f32x4*)(Xout + ro + bj * 32 + 4) = x1; }
;                     else { u32x4 w; w.x = cvt_pk_bf16(x0[0], x0[1]); w.y = cvt_pk_bf16(x0[2], x0[3]); w.z = cvt_pk_bf16(x1[0], x1[1]); w.w = cvt_pk_bf16(x1[2], x1[3]); *(u32x4*)(XB + ro + bj * 32) = w;
.LBB0_1074:
	v_lshl_add_u32 v152, s37, 8, v1
	v_lshl_or_b32 v156, s36, 8, v165
	v_ashrrev_i32_e32 v157, 31, v156
	v_ashrrev_i32_e32 v153, 31, v152
	v_lshl_add_u64 v[154:155], v[156:157], 1, s[68:69]
	v_lshlrev_b64 v[130:131], 12, v[152:153]
	v_or_b32_e32 v158, 16, v152
	v_lshl_add_u64 v[130:131], v[154:155], 0, v[130:131]
	v_ashrrev_i32_e32 v159, 31, v158
	global_load_dwordx4 v[168:171], v[130:131], off
	global_load_dwordx4 v[138:141], v[130:131], off offset:64
	v_lshlrev_b64 v[132:133], 12, v[158:159]
	v_lshl_add_u64 v[130:131], v[154:155], 0, v[132:133]
	global_load_dwordx4 v[134:137], v[130:131], off
	s_nop 0
	global_load_dwordx4 v[130:133], v[130:131], off offset:64
	v_or_b32_e32 v244, 32, v152
	v_or_b32_e32 v246, 48, v152
	v_ashrrev_i32_e32 v245, 31, v244
	v_ashrrev_i32_e32 v247, 31, v246
	v_lshlrev_b64 v[244:245], 12, v[244:245]
	v_lshlrev_b64 v[246:247], 12, v[246:247]
	v_lshl_add_u64 v[244:245], v[154:155], 0, v[244:245]
	v_lshl_add_u64 v[246:247], v[154:155], 0, v[246:247]
	global_load_dwordx4 v[176:179], v[244:245], off
	global_load_dwordx4 v[180:183], v[244:245], off offset:64
	global_load_dwordx4 v[206:209], v[246:247], off
	global_load_dwordx4 v[210:213], v[246:247], off offset:64
	s_nop 1
	v_add_u32_e32 v244, 0x80, v152
	v_add_u32_e32 v246, 0x90, v152
	v_ashrrev_i32_e32 v245, 31, v244
	v_ashrrev_i32_e32 v247, 31, v246
	v_lshlrev_b64 v[244:245], 12, v[244:245]
	v_lshlrev_b64 v[246:247], 12, v[246:247]
	v_lshl_add_u64 v[244:245], v[154:155], 0, v[244:245]
	v_lshl_add_u64 v[246:247], v[154:155], 0, v[246:247]
	global_load_dwordx4 v[214:217], v[244:245], off
	global_load_dwordx4 v[218:221], v[244:245], off offset:64
	global_load_dwordx4 v[236:239], v[246:247], off
	global_load_dwordx4 v[240:243], v[246:247], off offset:64
	v_cndmask_b32_e64 v160, 0, 1, s[80:81]
	v_cmp_ne_u32_e64 s[38:39], 1, v160
	v_lshlrev_b64 v[160:161], 11, v[152:153]
	v_lshl_add_u64 v[162:163], v[160:161], 0, v[156:157]
	s_mov_b64 s[46:47], -1
	s_andn2_b64 vcc, exec, s[80:81]
	v_lshl_add_u64 v[162:163], v[162:163], 2, s[62:63]
	s_waitcnt vmcnt(8)
	v_lshlrev_b32_e32 v172, 16, v168
	v_and_b32_e32 v173, 0xffff0000, v168
	v_lshlrev_b32_e32 v168, 16, v169
	v_and_b32_e32 v169, 0xffff0000, v169
	v_lshlrev_b32_e32 v174, 16, v170
	v_and_b32_e32 v175, 0xffff0000, v170
	v_lshlrev_b32_e32 v170, 16, v171
	v_and_b32_e32 v171, 0xffff0000, v171
	v_pk_add_f32 v[128:129], v[128:129], v[168:169]
	v_pk_add_f32 v[126:127], v[126:127], v[172:173]
	v_pk_add_f32 v[124:125], v[124:125], v[170:171]
	v_pk_add_f32 v[122:123], v[122:123], v[174:175]
	s_cbranch_vccnz .LBB0_1076
	s_mov_b64 s[46:47], 0
	global_store_dwordx4 v[162:163], v[126:129], off
	global_store_dwordx4 v[162:163], v[122:125], off offset:16

; __device__ __forceinline__ unsigned cvt_pk_bf16(float lo, float hi) { unsigned r; asm volatile("v_cvt_pk_bf16_f32 %0, %1, %2" : "=v"(r) : "v"(lo), "v"(hi)); return r; }
;     __device__ __forceinline__ void operator()(const f32x4 (&acc)[2][2][4][2], const Unit& u, int wr, int wc, int fr, int fq, int) const {
;     ...
;                     for (int bj = 0; bj < 2; ++bj) xr[mm][bj] = *(const u32x4*)(XB + (size_t)(row0 + ai * HALF + (m0 + mm) * 16) * ldc + col0 + bj * 32);
;             }
;             asm volatile("" ::: "memory");
; #pragma unroll
;             for (int mm = 0; mm < 2; ++mm) { const int m = m0 + mm; const int row = row0 + ai * HALF + m * 16; const size_t ro = (size_t)row * ldc + col0; float ss = 0.f;
; #pragma unroll
;                 for (int bj = 0; bj < 2; ++bj) { f32x4 x0, x1;
;                     if (Xin0) { x0 = xf[mm][bj][0]; x1 = xf[mm][bj][1]; }
;                     else { const u32x4 w = xr[mm][bj];
;                         x0 = (f32x4){__uint_as_float(w.x << 16), __uint_as_float(w.x & 0xffff0000u), __uint_as_float(w.y << 16), __uint_as_float(w.y & 0xffff0000u)};
;                         x1 = (f32x4){__uint_as_float(w.z << 16), __uint_as_float(w.z & 0xffff0000u), __uint_as_float(w.w << 16), __uint_as_float(w.w & 0xffff0000u)}; }
;                     x0 = x0 + acc[ai][bj][m][0]; x1 = x1 + acc[ai][bj][m][1];
;                     if (Xout) { *(f32x4*)(Xout + ro + bj * 32) = x0; *(f32x4*)(Xout + ro + bj * 32 + 4) = x1; }
;                     else { u32x4 w; w.x = cvt_pk_bf16(x0[0], x0[1]); w.y = cvt_pk_bf16(x0[2], x0[3]); w.z = cvt_pk_bf16(x1[0], x1[1]); w.w = cvt_pk_bf16(x1[2], x1[3]); *(u32x4*)(XB + ro + bj * 32) = w;
.LBB0_1098:
	v_or_b32_e32 v112, 32, v152
	v_ashrrev_i32_e32 v113, 31, v112
	v_or_b32_e32 v110, 48, v152
	s_waitcnt lgkmcnt(0)
	v_lshlrev_b64 v[98:99], 12, v[112:113]
	v_ashrrev_i32_e32 v111, 31, v110
	v_lshl_add_u64 v[98:99], v[154:155], 0, v[98:99]
	v_lshlrev_b64 v[100:101], 12, v[110:111]
	v_lshl_add_u64 v[100:101], v[154:155], 0, v[100:101]
	v_lshlrev_b64 v[112:113], 11, v[112:113]
	v_lshl_add_u64 v[118:119], v[112:113], 0, v[156:157]
	s_mov_b64 s[36:37], -1
	s_and_b64 vcc, exec, s[38:39]
	s_waitcnt vmcnt(8)
	v_lshlrev_b32_e32 v120, 16, v176
	v_and_b32_e32 v121, 0xffff0000, v176
	v_lshlrev_b32_e32 v114, 16, v177
	v_and_b32_e32 v115, 0xffff0000, v177
	v_lshlrev_b32_e32 v122, 16, v178
	v_and_b32_e32 v123, 0xffff0000, v178
	v_lshlrev_b32_e32 v116, 16, v179
	v_and_b32_e32 v117, 0xffff0000, v179
	v_pk_add_f32 v[96:97], v[96:97], v[114:115]
	v_pk_add_f32 v[94:95], v[94:95], v[120:121]
	v_pk_add_f32 v[92:93], v[92:93], v[116:117]
	v_pk_add_f32 v[90:91], v[90:91], v[122:123]
	v_lshl_add_u64 v[114:115], v[118:119], 2, s[62:63]
	s_cbranch_vccnz .LBB0_1100
	s_mov_b64 s[36:37], 0
	global_store_dwordx4 v[114:115], v[94:97], off
	global_store_dwordx4 v[114:115], v[90:93], off offset:16

; __device__ __forceinline__ unsigned cvt_pk_bf16(float lo, float hi) { unsigned r; asm volatile("v_cvt_pk_bf16_f32 %0, %1, %2" : "=v"(r) : "v"(lo), "v"(hi)); return r; }
;     __device__ __forceinline__ void operator()(const f32x4 (&acc)[2][2][4][2], const Unit& u, int wr, int wc, int fr, int fq, int) const {
;     ...
;                     else { const u32x4 w = xr[mm][bj];
;                         x0 = (f32x4){__uint_as_float(w.x << 16), __uint_as_float(w.x & 0xffff0000u), __uint_as_float(w.y << 16), __uint_as_float(w.y & 0xffff0000u)};
;                         x1 = (f32x4){__uint_as_float(w.z << 16), __uint_as_float(w.z & 0xffff0000u), __uint_as_float(w.w << 16), __uint_as_float(w.w & 0xffff0000u)}; }
;                     x0 = x0 + acc[ai][bj][m][0]; x1 = x1 + acc[ai][bj][m][1];
;                     if (Xout) { *(f32x4*)(Xout + ro + bj * 32) = x0; *(f32x4*)(Xout + ro + bj * 32 + 4) = x1; }
;                     else { u32x4 w; w.x = cvt_pk_bf16(x0[0], x0[1]); w.y = cvt_pk_bf16(x0[2], x0[3]); w.z = cvt_pk_bf16(x1[0], x1[1]); w.w = cvt_pk_bf16(x1[2], x1[3]); *(u32x4*)(XB + ro + bj * 32) = w;
.LBB0_1102:
	s_waitcnt vmcnt(8)
	v_lshlrev_b32_e32 v90, 16, v180
	v_and_b32_e32 v91, 0xffff0000, v180
	v_lshlrev_b32_e32 v92, 16, v181
	v_and_b32_e32 v93, 0xffff0000, v181
	v_lshlrev_b32_e32 v94, 16, v182
	v_and_b32_e32 v95, 0xffff0000, v182
	v_lshlrev_b32_e32 v96, 16, v183
	v_and_b32_e32 v97, 0xffff0000, v183
	v_pk_add_f32 v[88:89], v[88:89], v[92:93]
	v_pk_add_f32 v[86:87], v[86:87], v[90:91]
	v_pk_add_f32 v[84:85], v[84:85], v[96:97]
	v_pk_add_f32 v[82:83], v[82:83], v[94:95]
	s_and_b64 vcc, exec, s[38:39]
	s_mov_b64 s[36:37], -1
	s_cbranch_vccz .LBB0_1105
	s_andn2_b64 vcc, exec, s[36:37]
	s_cbranch_vccz .LBB0_1106

; __device__ __forceinline__ unsigned cvt_pk_bf16(float lo, float hi) { unsigned r; asm volatile("v_cvt_pk_bf16_f32 %0, %1, %2" : "=v"(r) : "v"(lo), "v"(hi)); return r; }
;     __device__ __forceinline__ void operator()(const f32x4 (&acc)[2][2][4][2], const Unit& u, int wr, int wc, int fr, int fq, int) const {
;     ...
;                     else { const u32x4 w = xr[mm][bj];
;                         x0 = (f32x4){__uint_as_float(w.x << 16), __uint_as_float(w.x & 0xffff0000u), __uint_as_float(w.y << 16), __uint_as_float(w.y & 0xffff0000u)};
;                         x1 = (f32x4){__uint_as_float(w.z << 16), __uint_as_float(w.z & 0xffff0000u), __uint_as_float(w.w << 16), __uint_as_float(w.w & 0xffff0000u)}; }
;                     x0 = x0 + acc[ai][bj][m][0]; x1 = x1 + acc[ai][bj][m][1];
;                     if (Xout) { *(f32x4*)(Xout + ro + bj * 32) = x0; *(f32x4*)(Xout + ro + bj * 32 + 4) = x1; }
;                     else { u32x4 w; w.x = cvt_pk_bf16(x0[0], x0[1]); w.y = cvt_pk_bf16(x0[2], x0[3]); w.z = cvt_pk_bf16(x1[0], x1[1]); w.w = cvt_pk_bf16(x1[2], x1[3]); *(u32x4*)(XB + ro + bj * 32) = w;
.LBB0_1110:
	s_waitcnt lgkmcnt(0)
	v_lshlrev_b64 v[82:83], 11, v[110:111]
	v_lshl_add_u64 v[84:85], v[82:83], 0, v[156:157]
	s_waitcnt vmcnt(8)
	v_lshlrev_b32_e32 v86, 16, v206
	v_and_b32_e32 v87, 0xffff0000, v206
	v_lshlrev_b32_e32 v88, 16, v207
	v_and_b32_e32 v89, 0xffff0000, v207
	v_lshlrev_b32_e32 v90, 16, v208
	v_and_b32_e32 v91, 0xffff0000, v208
	v_lshlrev_b32_e32 v92, 16, v209
	v_and_b32_e32 v93, 0xffff0000, v209
	v_pk_add_f32 v[80:81], v[80:81], v[88:89]
	v_pk_add_f32 v[78:79], v[78:79], v[86:87]
	v_pk_add_f32 v[76:77], v[76:77], v[92:93]
	v_pk_add_f32 v[74:75], v[74:75], v[90:91]
	s_mov_b64 s[36:37], -1
	s_and_b64 vcc, exec, s[38:39]
	v_lshl_add_u64 v[84:85], v[84:85], 2, s[62:63]
	s_cbranch_vccnz .LBB0_1112
	s_mov_b64 s[36:37], 0
	global_store_dwordx4 v[84:85], v[78:81], off
	global_store_dwordx4 v[84:85], v[74:77], off offset:16

; __device__ __forceinline__ unsigned cvt_pk_bf16(float lo, float hi) { unsigned r; asm volatile("v_cvt_pk_bf16_f32 %0, %1, %2" : "=v"(r) : "v"(lo), "v"(hi)); return r; }
;     __device__ __forceinline__ void operator()(const f32x4 (&acc)[2][2][4][2], const Unit& u, int wr, int wc, int fr, int fq, int) const {
;     ...
;                     else { const u32x4 w = xr[mm][bj];
;                         x0 = (f32x4){__uint_as_float(w.x << 16), __uint_as_float(w.x & 0xffff0000u), __uint_as_float(w.y << 16), __uint_as_float(w.y & 0xffff0000u)};
;                         x1 = (f32x4){__uint_as_float(w.z << 16), __uint_as_float(w.z & 0xffff0000u), __uint_as_float(w.w << 16), __uint_as_float(w.w & 0xffff0000u)}; }
;                     x0 = x0 + acc[ai][bj][m][0]; x1 = x1 + acc[ai][bj][m][1];
;                     if (Xout) { *(f32x4*)(Xout + ro + bj * 32) = x0; *(f32x4*)(Xout + ro + bj * 32 + 4) = x1; }
;                     else { u32x4 w; w.x = cvt_pk_bf16(x0[0], x0[1]); w.y = cvt_pk_bf16(x0[2], x0[3]); w.z = cvt_pk_bf16(x1[0], x1[1]); w.w = cvt_pk_bf16(x1[2], x1[3]); *(u32x4*)(XB + ro + bj * 32) = w;
.LBB0_1114:
	s_waitcnt vmcnt(8)
	v_lshlrev_b32_e32 v74, 16, v210
	v_and_b32_e32 v75, 0xffff0000, v210
	v_lshlrev_b32_e32 v76, 16, v211
	v_and_b32_e32 v77, 0xffff0000, v211
	v_lshlrev_b32_e32 v78, 16, v212
	v_and_b32_e32 v79, 0xffff0000, v212
	v_lshlrev_b32_e32 v80, 16, v213
	v_and_b32_e32 v81, 0xffff0000, v213
	v_pk_add_f32 v[72:73], v[72:73], v[76:77]
	v_pk_add_f32 v[70:71], v[70:71], v[74:75]
	v_pk_add_f32 v[68:69], v[68:69], v[80:81]
	v_pk_add_f32 v[66:67], v[66:67], v[78:79]
	s_and_b64 vcc, exec, s[38:39]
	s_mov_b64 s[36:37], -1
	s_cbranch_vccz .LBB0_1117
	s_andn2_b64 vcc, exec, s[36:37]
	s_cbranch_vccz .LBB0_1118

; __device__ __forceinline__ unsigned cvt_pk_bf16(float lo, float hi) { unsigned r; asm volatile("v_cvt_pk_bf16_f32 %0, %1, %2" : "=v"(r) : "v"(lo), "v"(hi)); return r; }
;     __device__ __forceinline__ void operator()(const f32x4 (&acc)[2][2][4][2], const Unit& u, int wr, int wc, int fr, int fq, int) const {
;     ...
;                     for (int bj = 0; bj < 2; ++bj) xr[mm][bj] = *(const u32x4*)(XB + (size_t)(row0 + ai * HALF + (m0 + mm) * 16) * ldc + col0 + bj * 32);
;             }
;             asm volatile("" ::: "memory");
; #pragma unroll
;             for (int mm = 0; mm < 2; ++mm) { const int m = m0 + mm; const int row = row0 + ai * HALF + m * 16; const size_t ro = (size_t)row * ldc + col0; float ss = 0.f;
; #pragma unroll
;                 for (int bj = 0; bj < 2; ++bj) { f32x4 x0, x1;
;                     if (Xin0) { x0 = xf[mm][bj][0]; x1 = xf[mm][bj][1]; }
;                     else { const u32x4 w = xr[mm][bj];
;                         x0 = (f32x4){__uint_as_float(w.x << 16), __uint_as_float(w.x & 0xffff0000u), __uint_as_float(w.y << 16), __uint_as_float(w.y & 0xffff0000u)};
;                         x1 = (f32x4){__uint_as_float(w.z << 16), __uint_as_float(w.z & 0xffff0000u), __uint_as_float(w.w << 16), __uint_as_float(w.w & 0xffff0000u)}; }
;                     x0 = x0 + acc[ai][bj][m][0]; x1 = x1 + acc[ai][bj][m][1];
;                     if (Xout) { *(f32x4*)(Xout + ro + bj * 32) = x0; *(f32x4*)(Xout + ro + bj * 32 + 4) = x1; }
;                     else { u32x4 w; w.x = cvt_pk_bf16(x0[0], x0[1]); w.y = cvt_pk_bf16(x0[2], x0[3]); w.z = cvt_pk_bf16(x1[0], x1[1]); w.w = cvt_pk_bf16(x1[2], x1[3]); *(u32x4*)(XB + ro + bj * 32) = w;
.LBB0_1122:
	v_add_u32_e32 v80, 0x80, v152
	v_ashrrev_i32_e32 v81, 31, v80
	v_add_u32_e32 v78, 0x90, v152
	s_waitcnt lgkmcnt(0)
	v_lshlrev_b64 v[66:67], 12, v[80:81]
	v_ashrrev_i32_e32 v79, 31, v78
	v_lshl_add_u64 v[66:67], v[154:155], 0, v[66:67]
	v_lshlrev_b64 v[68:69], 12, v[78:79]
	v_lshl_add_u64 v[68:69], v[154:155], 0, v[68:69]
	v_lshlrev_b64 v[80:81], 11, v[80:81]
	v_lshl_add_u64 v[86:87], v[80:81], 0, v[156:157]
	s_mov_b64 s[36:37], -1
	s_and_b64 vcc, exec, s[38:39]
	s_waitcnt vmcnt(8)
	v_lshlrev_b32_e32 v88, 16, v214
	v_and_b32_e32 v89, 0xffff0000, v214
	v_lshlrev_b32_e32 v82, 16, v215
	v_and_b32_e32 v83, 0xffff0000, v215
	v_lshlrev_b32_e32 v90, 16, v216
	v_and_b32_e32 v91, 0xffff0000, v216
	v_lshlrev_b32_e32 v84, 16, v217
	v_and_b32_e32 v85, 0xffff0000, v217
	v_pk_add_f32 v[64:65], v[64:65], v[82:83]
	v_pk_add_f32 v[62:63], v[62:63], v[88:89]
	v_pk_add_f32 v[60:61], v[60:61], v[84:85]
	v_pk_add_f32 v[58:59], v[58:59], v[90:91]
	v_lshl_add_u64 v[82:83], v[86:87], 2, s[62:63]
	s_cbranch_vccnz .LBB0_1124
	s_mov_b64 s[36:37], 0
	global_store_dwordx4 v[82:83], v[62:65], off
	global_store_dwordx4 v[82:83], v[58:61], off offset:16

; __device__ __forceinline__ unsigned cvt_pk_bf16(float lo, float hi) { unsigned r; asm volatile("v_cvt_pk_bf16_f32 %0, %1, %2" : "=v"(r) : "v"(lo), "v"(hi)); return r; }
;     __device__ __forceinline__ void operator()(const f32x4 (&acc)[2][2][4][2], const Unit& u, int wr, int wc, int fr, int fq, int) const {
;     ...
;                     else { const u32x4 w = xr[mm][bj];
;                         x0 = (f32x4){__uint_as_float(w.x << 16), __uint_as_float(w.x & 0xffff0000u), __uint_as_float(w.y << 16), __uint_as_float(w.y & 0xffff0000u)};
;                         x1 = (f32x4){__uint_as_float(w.z << 16), __uint_as_float(w.z & 0xffff0000u), __uint_as_float(w.w << 16), __uint_as_float(w.w & 0xffff0000u)}; }
;                     x0 = x0 + acc[ai][bj][m][0]; x1 = x1 + acc[ai][bj][m][1];
;                     if (Xout) { *(f32x4*)(Xout + ro + bj * 32) = x0; *(f32x4*)(Xout + ro + bj * 32 + 4) = x1; }
;                     else { u32x4 w; w.x = cvt_pk_bf16(x0[0], x0[1]); w.y = cvt_pk_bf16(x0[2], x0[3]); w.z = cvt_pk_bf16(x1[0], x1[1]); w.w = cvt_pk_bf16(x1[2], x1[3]); *(u32x4*)(XB + ro + bj * 32) = w;
.LBB0_1126:
	s_waitcnt vmcnt(8)
	v_lshlrev_b32_e32 v58, 16, v218
	v_and_b32_e32 v59, 0xffff0000, v218
	v_lshlrev_b32_e32 v60, 16, v219
	v_and_b32_e32 v61, 0xffff0000, v219
	v_lshlrev_b32_e32 v62, 16, v220
	v_and_b32_e32 v63, 0xffff0000, v220
	v_lshlrev_b32_e32 v64, 16, v221
	v_and_b32_e32 v65, 0xffff0000, v221
	v_pk_add_f32 v[56:57], v[56:57], v[60:61]
	v_pk_add_f32 v[54:55], v[54:55], v[58:59]
	v_pk_add_f32 v[52:53], v[52:53], v[64:65]
	v_pk_add_f32 v[50:51], v[50:51], v[62:63]
	s_and_b64 vcc, exec, s[38:39]
	s_mov_b64 s[36:37], -1
	s_cbranch_vccz .LBB0_1129
	s_andn2_b64 vcc, exec, s[36:37]
	s_cbranch_vccz .LBB0_1130

; __device__ __forceinline__ unsigned cvt_pk_bf16(float lo, float hi) { unsigned r; asm volatile("v_cvt_pk_bf16_f32 %0, %1, %2" : "=v"(r) : "v"(lo), "v"(hi)); return r; }
;     __device__ __forceinline__ void operator()(const f32x4 (&acc)[2][2][4][2], const Unit& u, int wr, int wc, int fr, int fq, int) const {
;     ...
;                     else { const u32x4 w = xr[mm][bj];
;                         x0 = (f32x4){__uint_as_float(w.x << 16), __uint_as_float(w.x & 0xffff0000u), __uint_as_float(w.y << 16), __uint_as_float(w.y & 0xffff0000u)};
;                         x1 = (f32x4){__uint_as_float(w.z << 16), __uint_as_float(w.z & 0xffff0000u), __uint_as_float(w.w << 16), __uint_as_float(w.w & 0xffff0000u)}; }
;                     x0 = x0 + acc[ai][bj][m][0]; x1 = x1 + acc[ai][bj][m][1];
;                     if (Xout) { *(f32x4*)(Xout + ro + bj * 32) = x0; *(f32x4*)(Xout + ro + bj * 32 + 4) = x1; }
;                     else { u32x4 w; w.x = cvt_pk_bf16(x0[0], x0[1]); w.y = cvt_pk_bf16(x0[2], x0[3]); w.z = cvt_pk_bf16(x1[0], x1[1]); w.w = cvt_pk_bf16(x1[2], x1[3]); *(u32x4*)(XB + ro + bj * 32) = w;
.LBB0_1134:
	s_waitcnt lgkmcnt(0)
	v_lshlrev_b64 v[50:51], 11, v[78:79]
	v_lshl_add_u64 v[52:53], v[50:51], 0, v[156:157]
	s_waitcnt vmcnt(8)
	v_lshlrev_b32_e32 v54, 16, v236
	v_and_b32_e32 v55, 0xffff0000, v236
	v_lshlrev_b32_e32 v56, 16, v237
	v_and_b32_e32 v57, 0xffff0000, v237
	v_lshlrev_b32_e32 v58, 16, v238
	v_and_b32_e32 v59, 0xffff0000, v238
	v_lshlrev_b32_e32 v60, 16, v239
	v_and_b32_e32 v61, 0xffff0000, v239
	v_pk_add_f32 v[48:49], v[48:49], v[56:57]
	v_pk_add_f32 v[46:47], v[46:47], v[54:55]
	v_pk_add_f32 v[44:45], v[44:45], v[60:61]
	v_pk_add_f32 v[42:43], v[42:43], v[58:59]
	s_mov_b64 s[36:37], -1
	s_and_b64 vcc, exec, s[38:39]
	v_lshl_add_u64 v[52:53], v[52:53], 2, s[62:63]
	s_cbranch_vccnz .LBB0_1136
	s_mov_b64 s[36:37], 0
	global_store_dwordx4 v[52:53], v[46:49], off
	global_store_dwordx4 v[52:53], v[42:45], off offset:16

; __device__ __forceinline__ unsigned cvt_pk_bf16(float lo, float hi) { unsigned r; asm volatile("v_cvt_pk_bf16_f32 %0, %1, %2" : "=v"(r) : "v"(lo), "v"(hi)); return r; }
;     __device__ __forceinline__ void operator()(const f32x4 (&acc)[2][2][4][2], const Unit& u, int wr, int wc, int fr, int fq, int) const {
;     ...
;                     else { const u32x4 w = xr[mm][bj];
;                         x0 = (f32x4){__uint_as_float(w.x << 16), __uint_as_float(w.x & 0xffff0000u), __uint_as_float(w.y << 16), __uint_as_float(w.y & 0xffff0000u)};
;                         x1 = (f32x4){__uint_as_float(w.z << 16), __uint_as_float(w.z & 0xffff0000u), __uint_as_float(w.w << 16), __uint_as_float(w.w & 0xffff0000u)}; }
;                     x0 = x0 + acc[ai][bj][m][0]; x1 = x1 + acc[ai][bj][m][1];
;                     if (Xout) { *(f32x4*)(Xout + ro + bj * 32) = x0; *(f32x4*)(Xout + ro + bj * 32 + 4) = x1; }
;                     else { u32x4 w; w.x = cvt_pk_bf16(x0[0], x0[1]); w.y = cvt_pk_bf16(x0[2], x0[3]); w.z = cvt_pk_bf16(x1[0], x1[1]); w.w = cvt_pk_bf16(x1[2], x1[3]); *(u32x4*)(XB + ro + bj * 32) = w;
.LBB0_1138:
	s_waitcnt vmcnt(8)
	v_lshlrev_b32_e32 v42, 16, v240
	v_and_b32_e32 v43, 0xffff0000, v240
	v_lshlrev_b32_e32 v44, 16, v241
	v_and_b32_e32 v45, 0xffff0000, v241
	v_lshlrev_b32_e32 v46, 16, v242
	v_and_b32_e32 v47, 0xffff0000, v242
	v_lshlrev_b32_e32 v48, 16, v243
	v_and_b32_e32 v49, 0xffff0000, v243
	v_pk_add_f32 v[40:41], v[40:41], v[44:45]
	v_pk_add_f32 v[38:39], v[38:39], v[42:43]
	v_pk_add_f32 v[36:37], v[36:37], v[48:49]
	v_pk_add_f32 v[34:35], v[34:35], v[46:47]
	s_and_b64 vcc, exec, s[38:39]
	s_mov_b64 s[36:37], -1
	s_cbranch_vccz .LBB0_1141
	s_andn2_b64 vcc, exec, s[36:37]
	s_cbranch_vccz .LBB0_1142
